# adaLN GEMV loop: all 16 weight loads of a step in flight at once (second eight hoisted into their own registers, counted waits re-derived)
# speedup vs baseline: 1.0125x; 1.0125x over previous
.LBB0_511:
	v_lshl_add_u64 v[18:19], v[60:61], 0, s[6:7]
	v_add_co_u32_e64 v36, s[0:1], s3, v18
	ds_read_b128 v[10:13], v63
	ds_read_b128 v[14:17], v63 offset:16
	ds_read_b128 v[2:5], v63 offset:32
	ds_read_b128 v[38:41], v63 offset:4096
	ds_read_b128 v[28:31], v63 offset:8192
	ds_read_b128 v[20:23], v63 offset:8208
	ds_read_b128 v[32:35], v63 offset:12288
	ds_read_b128 v[42:45], v63 offset:12304
	ds_read_b128 v[46:49], v63 offset:16384
	ds_read_b128 v[24:27], v63 offset:16400
	v_addc_co_u32_e64 v37, s[0:1], 0, v19, s[0:1]
	s_mov_b32 s0, 0xc000
	s_nop 0
	v_add_co_u32_e64 v64, s[0:1], s0, v18
	global_load_dword v62, v[18:19], off
	s_nop 0
	v_addc_co_u32_e64 v65, s[0:1], 0, v19, s[0:1]
	s_mov_b32 s0, 0x12000
	s_nop 0
	v_add_co_u32_e64 v66, s[0:1], s0, v18
	s_waitcnt lgkmcnt(0)
	v_mov_b32_e32 v80, v10
	v_addc_co_u32_e64 v67, s[0:1], 0, v19, s[0:1]
	s_mov_b32 s0, 0x18000
	s_nop 0
	v_add_co_u32_e64 v68, s[0:1], s0, v18
	v_mov_b32_e32 v81, v46
	s_nop 0
	v_addc_co_u32_e64 v69, s[0:1], 0, v19, s[0:1]
	s_mov_b32 s0, 0x1e000
	s_nop 0
	v_add_co_u32_e64 v70, s[0:1], s0, v18
	v_mov_b32_e32 v46, v11
	s_nop 0
	v_addc_co_u32_e64 v71, s[0:1], 0, v19, s[0:1]
	s_mov_b32 s0, 0x24000
	s_nop 0
	v_add_co_u32_e64 v72, s[0:1], s0, v18
	v_mov_b32_e32 v78, v32
	s_nop 0
	v_addc_co_u32_e64 v73, s[0:1], 0, v19, s[0:1]
	s_mov_b32 s0, 0x2a000
	s_nop 0
	v_add_co_u32_e64 v10, s[0:1], s0, v18
	v_mov_b32_e32 v79, v28
	s_nop 0
	v_addc_co_u32_e64 v11, s[0:1], 0, v19, s[0:1]
	global_load_dword v84, v[36:37], off
	s_nop 0
	global_load_dword v64, v[64:65], off
	s_nop 0
	global_load_dword v66, v[66:67], off
	s_nop 0
	global_load_dword v86, v[68:69], off
	global_load_dword v88, v[70:71], off
	global_load_dword v76, v[72:73], off
	global_load_dword v74, v[10:11], off
	s_mov_b64 s[100:101], 0x30000
	v_lshl_add_u64 v[116:117], v[18:19], 0, s[100:101]
	global_load_dword v100, v[116:117], off
	s_mov_b64 s[100:101], 0x36000
	v_lshl_add_u64 v[118:119], v[18:19], 0, s[100:101]
	global_load_dword v102, v[118:119], off
	s_mov_b64 s[100:101], 0x3c000
	v_lshl_add_u64 v[120:121], v[18:19], 0, s[100:101]
	global_load_dword v104, v[120:121], off
	s_mov_b64 s[100:101], 0x42000
	v_lshl_add_u64 v[122:123], v[18:19], 0, s[100:101]
	global_load_dword v106, v[122:123], off
	s_mov_b64 s[100:101], 0x48000
	v_lshl_add_u64 v[124:125], v[18:19], 0, s[100:101]
	global_load_dword v108, v[124:125], off
	s_mov_b64 s[100:101], 0x4e000
	v_lshl_add_u64 v[126:127], v[18:19], 0, s[100:101]
	global_load_dword v110, v[126:127], off
	s_mov_b64 s[100:101], 0x54000
	v_lshl_add_u64 v[128:129], v[18:19], 0, s[100:101]
	global_load_dword v112, v[128:129], off
	s_mov_b64 s[100:101], 0x5a000
	v_lshl_add_u64 v[90:91], v[18:19], 0, s[100:101]
	global_load_dword v114, v[90:91], off
	v_mov_b32_e32 v28, v33
	v_mov_b32_e32 v32, v34
	v_mov_b32_e32 v33, v30
	v_mov_b32_e32 v82, v12
	v_mov_b32_e32 v83, v48
	v_mov_b32_e32 v30, v35
	v_mov_b32_e32 v48, v13
	ds_read_b128 v[34:37], v63 offset:4112
	ds_read_b128 v[10:13], v63 offset:48
	s_add_u32 s6, s6, 0x60000
	s_addc_u32 s7, s7, 0
	s_cmp_eq_u32 s6, 0x600000
	s_waitcnt vmcnt(15)
	v_fmac_f32_e32 v55, v62, v38
	v_pk_fma_f32 v[8:9], v[62:63], v[78:79], v[8:9] op_sel_hi:[0,1,1]
	v_pk_fma_f32 v[6:7], v[62:63], v[80:81], v[6:7] op_sel_hi:[0,1,1]
	s_waitcnt vmcnt(14)
	v_fmac_f32_e32 v55, v84, v39
	v_pk_fma_f32 v[8:9], v[84:85], v[28:29], v[8:9] op_sel_hi:[0,1,1]
	v_pk_fma_f32 v[28:29], v[84:85], v[46:47], v[6:7] op_sel_hi:[0,1,1]
	s_waitcnt vmcnt(13)
	v_fmac_f32_e32 v55, v64, v40
	s_nop 0
	s_waitcnt vmcnt(12)
	v_fmac_f32_e32 v55, v66, v41
	v_pk_fma_f32 v[32:33], v[64:65], v[32:33], v[8:9] op_sel_hi:[0,1,1]
	v_pk_fma_f32 v[28:29], v[64:65], v[82:83], v[28:29] op_sel_hi:[0,1,1]
	v_pk_fma_f32 v[30:31], v[66:67], v[30:31], v[32:33] op_sel_hi:[0,1,1]
	s_nop 0
	s_nop 0
	v_pk_fma_f32 v[28:29], v[66:67], v[48:49], v[28:29] op_sel_hi:[0,1,1]
	s_nop 0
	s_nop 0
	ds_read_b128 v[6:9], v63 offset:4128
	s_nop 0
	s_nop 0
	s_waitcnt vmcnt(11) lgkmcnt(2)
	v_fmac_f32_e32 v55, v86, v34
	s_nop 0
	s_waitcnt vmcnt(10)
	v_fmac_f32_e32 v55, v88, v35
	s_nop 0
	s_nop 0
	s_nop 0
	v_mov_b32_e32 v18, v42
	v_mov_b32_e32 v19, v20
	v_mov_b32_e32 v38, v14
	v_mov_b32_e32 v39, v24
	v_mov_b32_e32 v20, v43
	v_mov_b32_e32 v24, v15
	v_pk_fma_f32 v[18:19], v[86:87], v[18:19], v[30:31] op_sel_hi:[0,1,1]
	v_pk_fma_f32 v[38:39], v[86:87], v[38:39], v[28:29] op_sel_hi:[0,1,1]
	v_mov_b32_e32 v32, v44
	v_mov_b32_e32 v33, v22
	v_mov_b32_e32 v42, v16
	v_mov_b32_e32 v43, v26
	v_pk_fma_f32 v[34:35], v[88:89], v[20:21], v[18:19] op_sel_hi:[0,1,1]
	v_pk_fma_f32 v[24:25], v[88:89], v[24:25], v[38:39] op_sel_hi:[0,1,1]
	v_mov_b32_e32 v22, v45
	v_mov_b32_e32 v26, v17
	ds_read_b128 v[14:17], v63 offset:8224
	ds_read_b128 v[28:31], v63 offset:12320
	ds_read_b128 v[18:21], v63 offset:16416
	s_waitcnt vmcnt(9)
	v_pk_fma_f32 v[40:41], v[76:77], v[32:33], v[34:35] op_sel_hi:[0,1,1]
	v_pk_fma_f32 v[24:25], v[76:77], v[42:43], v[24:25] op_sel_hi:[0,1,1]
	v_fmac_f32_e32 v55, v76, v36
	s_waitcnt vmcnt(8)
	v_fmac_f32_e32 v55, v74, v37
	ds_read_b128 v[36:39], v63 offset:8240
	v_pk_fma_f32 v[44:45], v[74:75], v[22:23], v[40:41] op_sel_hi:[0,1,1]
	ds_read_b128 v[40:43], v63 offset:12336
	v_pk_fma_f32 v[26:27], v[74:75], v[26:27], v[24:25] op_sel_hi:[0,1,1]
	ds_read_b128 v[22:25], v63 offset:16432
	ds_read_b128 v[32:35], v63 offset:4144
	s_waitcnt lgkmcnt(5)
	v_mov_b32_e32 v74, v28
	v_mov_b32_e32 v75, v14
	v_mov_b32_e32 v14, v29
	v_mov_b32_e32 v28, v30
	v_mov_b32_e32 v29, v16
	v_mov_b32_e32 v16, v31
	v_mov_b32_e32 v30, v2
	s_waitcnt lgkmcnt(4)
	v_mov_b32_e32 v31, v18
	v_mov_b32_e32 v18, v3
	v_mov_b32_e32 v2, v4
	v_mov_b32_e32 v3, v20
	v_mov_b32_e32 v20, v5
	s_waitcnt lgkmcnt(2)
	v_mov_b32_e32 v4, v40
	v_mov_b32_e32 v5, v36
	v_mov_b32_e32 v36, v41
	v_mov_b32_e32 v40, v42
	v_mov_b32_e32 v41, v38
	v_mov_b32_e32 v38, v43
	v_mov_b32_e32 v42, v10
	s_waitcnt lgkmcnt(1)
	v_mov_b32_e32 v43, v22
	v_mov_b32_e32 v22, v11
	v_mov_b32_e32 v10, v12
	v_mov_b32_e32 v11, v24
	v_mov_b32_e32 v24, v13
	v_add_u32_e32 v63, 64, v63
	s_waitcnt vmcnt(7)
	v_fmac_f32_e32 v55, v100, v6
	v_pk_fma_f32 v[12:13], v[100:101], v[74:75], v[44:45] op_sel_hi:[0,1,1]
	v_pk_fma_f32 v[26:27], v[100:101], v[30:31], v[26:27] op_sel_hi:[0,1,1]
	s_waitcnt vmcnt(6)
	v_fmac_f32_e32 v55, v102, v7
	v_pk_fma_f32 v[6:7], v[102:103], v[14:15], v[12:13] op_sel_hi:[0,1,1]
	v_pk_fma_f32 v[12:13], v[102:103], v[18:19], v[26:27] op_sel_hi:[0,1,1]
	s_waitcnt vmcnt(5)
	v_fmac_f32_e32 v55, v104, v8
	v_pk_fma_f32 v[6:7], v[104:105], v[28:29], v[6:7] op_sel_hi:[0,1,1]
	v_pk_fma_f32 v[2:3], v[104:105], v[2:3], v[12:13] op_sel_hi:[0,1,1]
	s_waitcnt vmcnt(4)
	v_fmac_f32_e32 v55, v106, v9
	v_pk_fma_f32 v[6:7], v[106:107], v[16:17], v[6:7] op_sel_hi:[0,1,1]
	v_pk_fma_f32 v[2:3], v[106:107], v[20:21], v[2:3] op_sel_hi:[0,1,1]
	s_waitcnt vmcnt(3) lgkmcnt(0)
	v_fmac_f32_e32 v55, v108, v32
	v_pk_fma_f32 v[4:5], v[108:109], v[4:5], v[6:7] op_sel_hi:[0,1,1]
	v_pk_fma_f32 v[2:3], v[108:109], v[42:43], v[2:3] op_sel_hi:[0,1,1]
	s_waitcnt vmcnt(2)
	v_fmac_f32_e32 v55, v110, v33
	v_pk_fma_f32 v[4:5], v[110:111], v[36:37], v[4:5] op_sel_hi:[0,1,1]
	v_pk_fma_f32 v[2:3], v[110:111], v[22:23], v[2:3] op_sel_hi:[0,1,1]
	s_waitcnt vmcnt(1)
	v_fmac_f32_e32 v55, v112, v34
	v_pk_fma_f32 v[4:5], v[112:113], v[40:41], v[4:5] op_sel_hi:[0,1,1]
	v_pk_fma_f32 v[2:3], v[112:113], v[10:11], v[2:3] op_sel_hi:[0,1,1]
	s_waitcnt vmcnt(0)
	v_fmac_f32_e32 v55, v114, v35
	v_pk_fma_f32 v[8:9], v[114:115], v[38:39], v[4:5] op_sel_hi:[0,1,1]
	v_pk_fma_f32 v[6:7], v[114:115], v[24:25], v[2:3] op_sel_hi:[0,1,1]
	s_cbranch_scc0 .LBB0_511
	ds_write_b32 v54, v6 offset:20480
	ds_write2st64_b32 v53, v55, v9 offset0:81 offset1:82
	ds_write2st64_b32 v53, v8, v7 offset0:83 offset1:84
	s_waitcnt lgkmcnt(0)
	s_barrier
	s_and_saveexec_b64 s[0:1], vcc
	s_cbranch_execz .LBB0_509
	s_mul_i32 s6, s13, 0x1800
	s_add_i32 s6, s6, s4
	v_or_b32_e32 v2, s6, v50
	v_readlane_b32 s36, v254, 27
	v_ashrrev_i32_e32 v3, 31, v2
	v_readlane_b32 s38, v254, 29
	v_readlane_b32 s39, v254, 30
	s_mul_i32 s6, s13, 5
	s_add_i32 s7, s6, 2
	v_lshl_add_u64 v[2:3], v[2:3], 2, s[38:39]
	global_load_dword v32, v[2:3], off
	ds_read2st64_b32 v[4:5], v52 offset0:80 offset1:81
	ds_read2st64_b32 v[6:7], v52 offset0:84 offset1:85
	ds_read2st64_b32 v[8:9], v52 offset0:86 offset1:87
	ds_read2st64_b32 v[10:11], v52 offset0:82 offset1:83
	ds_read2st64_b32 v[12:13], v52 offset0:90 offset1:91
	ds_read2st64_b32 v[14:15], v52 offset0:94 offset1:95
	ds_read2st64_b32 v[16:17], v52 offset0:92 offset1:93
	ds_read2st64_b32 v[18:19], v52 offset0:88 offset1:89
	ds_read2st64_b32 v[20:21], v52 offset0:96 offset1:97
	ds_read2st64_b32 v[22:23], v52 offset0:98 offset1:99
	s_waitcnt lgkmcnt(8)
	v_add_f32_e32 v4, v4, v7
	v_lshl_add_u64 v[2:3], s[4:5], 2, v[56:57]
	s_waitcnt lgkmcnt(7)
	v_add_f32_e32 v5, v5, v8
	s_waitcnt lgkmcnt(6)
	v_add_f32_e32 v7, v10, v9
	s_waitcnt lgkmcnt(2)
	v_add_f32_e32 v8, v11, v18
	v_add_f32_e32 v6, v6, v19
	v_add_f32_e32 v4, v4, v12
	v_mad_i64_i32 v[24:25], s[4:5], s6, v204, v[2:3]
	v_add_f32_e32 v5, v5, v13
	v_add_f32_e32 v7, v7, v16
	v_add_f32_e32 v8, v8, v17
	v_add_f32_e32 v6, v6, v14
	v_add_f32_e32 v4, v4, v15
	s_add_i32 s4, s6, 1
	s_add_i32 s13, s6, 3
	s_add_i32 s6, s6, 4
	s_waitcnt lgkmcnt(1)
	v_add_f32_e32 v5, v5, v20
	v_add_f32_e32 v7, v7, v21
	s_waitcnt lgkmcnt(0)
	v_add_f32_e32 v8, v8, v22
	v_add_f32_e32 v6, v6, v23
	v_readlane_b32 s37, v254, 28
	v_readlane_b32 s40, v254, 31
	v_readlane_b32 s41, v254, 32
	v_readlane_b32 s42, v254, 33
	v_readlane_b32 s43, v254, 34
	v_readlane_b32 s44, v254, 35
	v_readlane_b32 s45, v254, 36
	v_readlane_b32 s46, v254, 37
	v_readlane_b32 s47, v254, 38
	v_readlane_b32 s48, v254, 39
	v_readlane_b32 s49, v254, 40
	v_readlane_b32 s50, v254, 41
	v_readlane_b32 s51, v254, 42
	v_mad_i64_i32 v[26:27], s[4:5], s4, v204, v[2:3]
	v_mad_i64_i32 v[28:29], s[4:5], s7, v204, v[2:3]
	v_mad_i64_i32 v[30:31], s[4:5], s13, v204, v[2:3]
	v_mad_i64_i32 v[2:3], s[4:5], s6, v204, v[2:3]
	s_waitcnt vmcnt(0)
	v_add_f32_e32 v4, v32, v4
	v_add_f32_e32 v5, v32, v5
	v_add_f32_e32 v7, v32, v7
	v_add_f32_e32 v8, v32, v8
	v_add_f32_e32 v6, v32, v6
	global_store_dword v[24:25], v4, off
	global_store_dword v[26:27], v5, off
	global_store_dword v[28:29], v7, off
	global_store_dword v[30:31], v8, off
	global_store_dword v[2:3], v6, off
	s_branch .LBB0_509
